# plus residual epilogue variants for first out-proj (f32 x input) and last W2 (f32 output): permlane16 swap + dwordx4
# speedup vs baseline: 1.0066x; 1.0066x over previous
.LBB0_71:
	s_mov_b64 s[24:25], 0
	s_cbranch_execz .LBB0_69
	v_readlane_b32 s48, v254, 0
	v_readlane_b32 s49, v254, 1
	v_and_b32_e32 v230, 16, v225
	v_readlane_b32 s26, v255, 35
	v_readlane_b32 s27, v255, 36
	v_lshrrev_b32_e32 v219, 1, v230
	v_add_u32_e32 v230, v230, v219
	v_add_co_u32_e32 v164, vcc, v198, v230
	s_lshl_b32 s2, s45, 4
	s_nop 0
	v_addc_co_u32_e32 v165, vcc, 0, v199, vcc
	v_add_co_u32_e32 v166, vcc, v196, v230
	s_lshl_b32 s3, s41, 2
	s_nop 0
	v_addc_co_u32_e32 v167, vcc, 0, v197, vcc
	s_add_i32 s2, s2, s3
	v_lshlrev_b32_e32 v219, 1, v230
	v_lshl_add_u64 v[170:171], v[128:129], 2, s[48:49]
	s_nop 0
	v_add_co_u32_e32 v170, vcc, v170, v219
	s_nop 1
	v_addc_co_u32_e32 v171, vcc, 0, v171, vcc
	v_mov_b32_e32 v168, v170
	v_mov_b32_e32 v169, v171
	global_load_dwordx4 v[132:135], v[168:169], off
	global_load_dwordx4 v[136:139], v[168:169], off offset:16
	global_load_dwordx4 v[140:143], v[168:169], off offset:512
	global_load_dwordx4 v[144:147], v[168:169], off offset:528
	v_add_co_u32_e32 v168, vcc, 0x20000, v170
	s_nop 1
	v_addc_co_u32_e32 v169, vcc, 0, v171, vcc
	global_load_dwordx4 v[148:151], v[168:169], off
	global_load_dwordx4 v[152:155], v[168:169], off offset:16
	global_load_dwordx4 v[156:159], v[168:169], off offset:512
	global_load_dwordx4 v[160:163], v[168:169], off offset:528
	v_add_co_u32_e32 v168, vcc, 0x40000, v170
	s_nop 1
	v_addc_co_u32_e32 v169, vcc, 0, v171, vcc
	global_load_dwordx4 v[200:203], v[168:169], off
	global_load_dwordx4 v[204:207], v[168:169], off offset:16
	global_load_dwordx4 v[208:211], v[168:169], off offset:512
	global_load_dwordx4 v[212:215], v[168:169], off offset:528
	v_lshlrev_b32_e32 v230, 7, v194
	v_add_u32_e32 v230, s2, v230
	v_mov_b32_e32 v173, s27
	v_add_co_u32_e32 v172, vcc, s26, v230
	s_nop 1
	v_addc_co_u32_e32 v173, vcc, 0, v173, vcc
	v_mov_b32_e32 v128, v164
	v_mov_b32_e32 v129, v165
	v_mov_b32_e32 v130, v166
	v_mov_b32_e32 v131, v167
	v_permlane16_swap_b32_e32 v124, v120
	v_permlane16_swap_b32_e32 v125, v121
	v_permlane16_swap_b32_e32 v126, v122
	v_permlane16_swap_b32_e32 v127, v123
	s_waitcnt vmcnt(11)
	v_pk_add_f32 v[124:125], v[132:133], v[124:125]
	v_pk_add_f32 v[126:127], v[134:135], v[126:127]
	s_waitcnt vmcnt(10)
	v_pk_add_f32 v[120:121], v[136:137], v[120:121]
	v_pk_add_f32 v[122:123], v[138:139], v[122:123]
	v_cvt_pk_bf16_f32 v132, v124, v125
	v_cvt_pk_bf16_f32 v133, v126, v127
	v_cvt_pk_bf16_f32 v134, v120, v121
	v_cvt_pk_bf16_f32 v135, v122, v123
	global_store_dwordx4 v[128:129], v[132:135], off
	v_lshlrev_b32_e32 v216, 16, v132
	v_and_b32_e32 v217, 0xffff0000, v132
	v_pk_add_f32 v[216:217], v[124:125], v[216:217] neg_lo:[0,1] neg_hi:[0,1]
	v_pk_mul_f32 v[228:229], v[124:125], v[124:125]
	v_cvt_pk_bf16_f32 v136, v216, v217
	v_lshlrev_b32_e32 v216, 16, v133
	v_and_b32_e32 v217, 0xffff0000, v133
	v_pk_add_f32 v[216:217], v[126:127], v[216:217] neg_lo:[0,1] neg_hi:[0,1]
	v_pk_fma_f32 v[228:229], v[126:127], v[126:127], v[228:229]
	v_cvt_pk_bf16_f32 v137, v216, v217
	v_lshlrev_b32_e32 v216, 16, v134
	v_and_b32_e32 v217, 0xffff0000, v134
	v_pk_add_f32 v[216:217], v[120:121], v[216:217] neg_lo:[0,1] neg_hi:[0,1]
	v_pk_fma_f32 v[228:229], v[120:121], v[120:121], v[228:229]
	v_cvt_pk_bf16_f32 v138, v216, v217
	v_lshlrev_b32_e32 v216, 16, v135
	v_and_b32_e32 v217, 0xffff0000, v135
	v_pk_add_f32 v[216:217], v[122:123], v[216:217] neg_lo:[0,1] neg_hi:[0,1]
	v_pk_fma_f32 v[228:229], v[122:123], v[122:123], v[228:229]
	v_cvt_pk_bf16_f32 v139, v216, v217
	global_store_dwordx4 v[130:131], v[136:139], off
	v_permlane16_swap_b32_e32 v116, v112
	v_permlane16_swap_b32_e32 v117, v113
	v_permlane16_swap_b32_e32 v118, v114
	v_permlane16_swap_b32_e32 v119, v115
	s_waitcnt vmcnt(11)
	v_pk_add_f32 v[116:117], v[140:141], v[116:117]
	v_pk_add_f32 v[118:119], v[142:143], v[118:119]
	s_waitcnt vmcnt(10)
	v_pk_add_f32 v[112:113], v[144:145], v[112:113]
	v_pk_add_f32 v[114:115], v[146:147], v[114:115]
	v_cvt_pk_bf16_f32 v140, v116, v117
	v_cvt_pk_bf16_f32 v141, v118, v119
	v_cvt_pk_bf16_f32 v142, v112, v113
	v_cvt_pk_bf16_f32 v143, v114, v115
	global_store_dwordx4 v[128:129], v[140:143], off offset:256
	v_lshlrev_b32_e32 v216, 16, v140
	v_and_b32_e32 v217, 0xffff0000, v140
	v_pk_add_f32 v[216:217], v[116:117], v[216:217] neg_lo:[0,1] neg_hi:[0,1]
	v_pk_fma_f32 v[228:229], v[116:117], v[116:117], v[228:229]
	v_cvt_pk_bf16_f32 v144, v216, v217
	v_lshlrev_b32_e32 v216, 16, v141
	v_and_b32_e32 v217, 0xffff0000, v141
	v_pk_add_f32 v[216:217], v[118:119], v[216:217] neg_lo:[0,1] neg_hi:[0,1]
	v_pk_fma_f32 v[228:229], v[118:119], v[118:119], v[228:229]
	v_cvt_pk_bf16_f32 v145, v216, v217
	v_lshlrev_b32_e32 v216, 16, v142
	v_and_b32_e32 v217, 0xffff0000, v142
	v_pk_add_f32 v[216:217], v[112:113], v[216:217] neg_lo:[0,1] neg_hi:[0,1]
	v_pk_fma_f32 v[228:229], v[112:113], v[112:113], v[228:229]
	v_cvt_pk_bf16_f32 v146, v216, v217
	v_lshlrev_b32_e32 v216, 16, v143
	v_and_b32_e32 v217, 0xffff0000, v143
	v_pk_add_f32 v[216:217], v[114:115], v[216:217] neg_lo:[0,1] neg_hi:[0,1]
	v_pk_fma_f32 v[228:229], v[114:115], v[114:115], v[228:229]
	v_cvt_pk_bf16_f32 v147, v216, v217
	global_store_dwordx4 v[130:131], v[144:147], off offset:256
	v_add_f32_e32 v230, v228, v229
	v_mov_b32_e32 v219, v230
	s_nop 1
	v_permlane16_swap_b32_e32 v219, v230
	v_add_f32_e32 v230, v230, v219
	v_mov_b32_e32 v219, v230
	s_nop 1
	v_permlane32_swap_b32_e32 v219, v230
	v_add_f32_e32 v230, v230, v219
	v_mov_b32_e32 v174, v172
	v_mov_b32_e32 v175, v173
	s_and_saveexec_b64 s[24:25], s[14:15]
	global_store_dword v[174:175], v230, off
	s_mov_b64 exec, s[24:25]
	v_add_co_u32_e32 v168, vcc, 0x60000, v170
	s_nop 1
	v_addc_co_u32_e32 v169, vcc, 0, v171, vcc
	global_load_dwordx4 v[132:135], v[168:169], off
	global_load_dwordx4 v[136:139], v[168:169], off offset:16
	global_load_dwordx4 v[140:143], v[168:169], off offset:512
	global_load_dwordx4 v[144:147], v[168:169], off offset:528
	v_add_co_u32_e32 v128, vcc, 0x10000, v164
	s_nop 1
	v_addc_co_u32_e32 v129, vcc, 0, v165, vcc
	v_add_co_u32_e32 v130, vcc, 0x10000, v166
	s_nop 1
	v_addc_co_u32_e32 v131, vcc, 0, v167, vcc
	v_permlane16_swap_b32_e32 v108, v104
	v_permlane16_swap_b32_e32 v109, v105
	v_permlane16_swap_b32_e32 v110, v106
	v_permlane16_swap_b32_e32 v111, v107
	s_waitcnt vmcnt(16)
	v_pk_add_f32 v[108:109], v[148:149], v[108:109]
	v_pk_add_f32 v[110:111], v[150:151], v[110:111]
	s_waitcnt vmcnt(15)
	v_pk_add_f32 v[104:105], v[152:153], v[104:105]
	v_pk_add_f32 v[106:107], v[154:155], v[106:107]
	v_cvt_pk_bf16_f32 v148, v108, v109
	v_cvt_pk_bf16_f32 v149, v110, v111
	v_cvt_pk_bf16_f32 v150, v104, v105
	v_cvt_pk_bf16_f32 v151, v106, v107
	global_store_dwordx4 v[128:129], v[148:151], off
	v_lshlrev_b32_e32 v216, 16, v148
	v_and_b32_e32 v217, 0xffff0000, v148
	v_pk_add_f32 v[216:217], v[108:109], v[216:217] neg_lo:[0,1] neg_hi:[0,1]
	v_pk_mul_f32 v[228:229], v[108:109], v[108:109]
	v_cvt_pk_bf16_f32 v152, v216, v217
	v_lshlrev_b32_e32 v216, 16, v149
	v_and_b32_e32 v217, 0xffff0000, v149
	v_pk_add_f32 v[216:217], v[110:111], v[216:217] neg_lo:[0,1] neg_hi:[0,1]
	v_pk_fma_f32 v[228:229], v[110:111], v[110:111], v[228:229]
	v_cvt_pk_bf16_f32 v153, v216, v217
	v_lshlrev_b32_e32 v216, 16, v150
	v_and_b32_e32 v217, 0xffff0000, v150
	v_pk_add_f32 v[216:217], v[104:105], v[216:217] neg_lo:[0,1] neg_hi:[0,1]
	v_pk_fma_f32 v[228:229], v[104:105], v[104:105], v[228:229]
	v_cvt_pk_bf16_f32 v154, v216, v217
	v_lshlrev_b32_e32 v216, 16, v151
	v_and_b32_e32 v217, 0xffff0000, v151
	v_pk_add_f32 v[216:217], v[106:107], v[216:217] neg_lo:[0,1] neg_hi:[0,1]
	v_pk_fma_f32 v[228:229], v[106:107], v[106:107], v[228:229]
	v_cvt_pk_bf16_f32 v155, v216, v217
	global_store_dwordx4 v[130:131], v[152:155], off
	v_permlane16_swap_b32_e32 v100, v96
	v_permlane16_swap_b32_e32 v101, v97
	v_permlane16_swap_b32_e32 v102, v98
	v_permlane16_swap_b32_e32 v103, v99
	s_waitcnt vmcnt(16)
	v_pk_add_f32 v[100:101], v[156:157], v[100:101]
	v_pk_add_f32 v[102:103], v[158:159], v[102:103]
	s_waitcnt vmcnt(15)
	v_pk_add_f32 v[96:97], v[160:161], v[96:97]
	v_pk_add_f32 v[98:99], v[162:163], v[98:99]
	v_cvt_pk_bf16_f32 v156, v100, v101
	v_cvt_pk_bf16_f32 v157, v102, v103
	v_cvt_pk_bf16_f32 v158, v96, v97
	v_cvt_pk_bf16_f32 v159, v98, v99
	global_store_dwordx4 v[128:129], v[156:159], off offset:256
	v_lshlrev_b32_e32 v216, 16, v156
	v_and_b32_e32 v217, 0xffff0000, v156
	v_pk_add_f32 v[216:217], v[100:101], v[216:217] neg_lo:[0,1] neg_hi:[0,1]
	v_pk_fma_f32 v[228:229], v[100:101], v[100:101], v[228:229]
	v_cvt_pk_bf16_f32 v160, v216, v217
	v_lshlrev_b32_e32 v216, 16, v157
	v_and_b32_e32 v217, 0xffff0000, v157
	v_pk_add_f32 v[216:217], v[102:103], v[216:217] neg_lo:[0,1] neg_hi:[0,1]
	v_pk_fma_f32 v[228:229], v[102:103], v[102:103], v[228:229]
	v_cvt_pk_bf16_f32 v161, v216, v217
	v_lshlrev_b32_e32 v216, 16, v158
	v_and_b32_e32 v217, 0xffff0000, v158
	v_pk_add_f32 v[216:217], v[96:97], v[216:217] neg_lo:[0,1] neg_hi:[0,1]
	v_pk_fma_f32 v[228:229], v[96:97], v[96:97], v[228:229]
	v_cvt_pk_bf16_f32 v162, v216, v217
	v_lshlrev_b32_e32 v216, 16, v159
	v_and_b32_e32 v217, 0xffff0000, v159
	v_pk_add_f32 v[216:217], v[98:99], v[216:217] neg_lo:[0,1] neg_hi:[0,1]
	v_pk_fma_f32 v[228:229], v[98:99], v[98:99], v[228:229]
	v_cvt_pk_bf16_f32 v163, v216, v217
	global_store_dwordx4 v[130:131], v[160:163], off offset:256
	v_add_f32_e32 v230, v228, v229
	v_mov_b32_e32 v219, v230
	s_nop 1
	v_permlane16_swap_b32_e32 v219, v230
	v_add_f32_e32 v230, v230, v219
	v_mov_b32_e32 v219, v230
	s_nop 1
	v_permlane32_swap_b32_e32 v219, v230
	v_add_f32_e32 v230, v230, v219
	v_add_co_u32_e32 v174, vcc, 0x800, v172
	s_nop 1
	v_addc_co_u32_e32 v175, vcc, 0, v173, vcc
	s_and_saveexec_b64 s[24:25], s[14:15]
	global_store_dword v[174:175], v230, off
	s_mov_b64 exec, s[24:25]
	v_add_co_u32_e32 v168, vcc, 0x100000, v170
	s_nop 1
	v_addc_co_u32_e32 v169, vcc, 0, v171, vcc
	global_load_dwordx4 v[148:151], v[168:169], off
	global_load_dwordx4 v[152:155], v[168:169], off offset:16
	global_load_dwordx4 v[156:159], v[168:169], off offset:512
	global_load_dwordx4 v[160:163], v[168:169], off offset:528
	v_add_co_u32_e32 v128, vcc, 0x20000, v164
	s_nop 1
	v_addc_co_u32_e32 v129, vcc, 0, v165, vcc
	v_add_co_u32_e32 v130, vcc, 0x20000, v166
	s_nop 1
	v_addc_co_u32_e32 v131, vcc, 0, v167, vcc
	v_permlane16_swap_b32_e32 v92, v88
	v_permlane16_swap_b32_e32 v93, v89
	v_permlane16_swap_b32_e32 v94, v90
	v_permlane16_swap_b32_e32 v95, v91
	s_waitcnt vmcnt(21)
	v_pk_add_f32 v[92:93], v[200:201], v[92:93]
	v_pk_add_f32 v[94:95], v[202:203], v[94:95]
	s_waitcnt vmcnt(20)
	v_pk_add_f32 v[88:89], v[204:205], v[88:89]
	v_pk_add_f32 v[90:91], v[206:207], v[90:91]
	v_cvt_pk_bf16_f32 v200, v92, v93
	v_cvt_pk_bf16_f32 v201, v94, v95
	v_cvt_pk_bf16_f32 v202, v88, v89
	v_cvt_pk_bf16_f32 v203, v90, v91
	global_store_dwordx4 v[128:129], v[200:203], off
	v_lshlrev_b32_e32 v216, 16, v200
	v_and_b32_e32 v217, 0xffff0000, v200
	v_pk_add_f32 v[216:217], v[92:93], v[216:217] neg_lo:[0,1] neg_hi:[0,1]
	v_pk_mul_f32 v[228:229], v[92:93], v[92:93]
	v_cvt_pk_bf16_f32 v204, v216, v217
	v_lshlrev_b32_e32 v216, 16, v201
	v_and_b32_e32 v217, 0xffff0000, v201
	v_pk_add_f32 v[216:217], v[94:95], v[216:217] neg_lo:[0,1] neg_hi:[0,1]
	v_pk_fma_f32 v[228:229], v[94:95], v[94:95], v[228:229]
	v_cvt_pk_bf16_f32 v205, v216, v217
	v_lshlrev_b32_e32 v216, 16, v202
	v_and_b32_e32 v217, 0xffff0000, v202
	v_pk_add_f32 v[216:217], v[88:89], v[216:217] neg_lo:[0,1] neg_hi:[0,1]
	v_pk_fma_f32 v[228:229], v[88:89], v[88:89], v[228:229]
	v_cvt_pk_bf16_f32 v206, v216, v217
	v_lshlrev_b32_e32 v216, 16, v203
	v_and_b32_e32 v217, 0xffff0000, v203
	v_pk_add_f32 v[216:217], v[90:91], v[216:217] neg_lo:[0,1] neg_hi:[0,1]
	v_pk_fma_f32 v[228:229], v[90:91], v[90:91], v[228:229]
	v_cvt_pk_bf16_f32 v207, v216, v217
	global_store_dwordx4 v[130:131], v[204:207], off
	v_permlane16_swap_b32_e32 v84, v80
	v_permlane16_swap_b32_e32 v85, v81
	v_permlane16_swap_b32_e32 v86, v82
	v_permlane16_swap_b32_e32 v87, v83
	s_waitcnt vmcnt(21)
	v_pk_add_f32 v[84:85], v[208:209], v[84:85]
	v_pk_add_f32 v[86:87], v[210:211], v[86:87]
	s_waitcnt vmcnt(20)
	v_pk_add_f32 v[80:81], v[212:213], v[80:81]
	v_pk_add_f32 v[82:83], v[214:215], v[82:83]
	v_cvt_pk_bf16_f32 v208, v84, v85
	v_cvt_pk_bf16_f32 v209, v86, v87
	v_cvt_pk_bf16_f32 v210, v80, v81
	v_cvt_pk_bf16_f32 v211, v82, v83
	global_store_dwordx4 v[128:129], v[208:211], off offset:256
	v_lshlrev_b32_e32 v216, 16, v208
	v_and_b32_e32 v217, 0xffff0000, v208
	v_pk_add_f32 v[216:217], v[84:85], v[216:217] neg_lo:[0,1] neg_hi:[0,1]
	v_pk_fma_f32 v[228:229], v[84:85], v[84:85], v[228:229]
	v_cvt_pk_bf16_f32 v212, v216, v217
	v_lshlrev_b32_e32 v216, 16, v209
	v_and_b32_e32 v217, 0xffff0000, v209
	v_pk_add_f32 v[216:217], v[86:87], v[216:217] neg_lo:[0,1] neg_hi:[0,1]
	v_pk_fma_f32 v[228:229], v[86:87], v[86:87], v[228:229]
	v_cvt_pk_bf16_f32 v213, v216, v217
	v_lshlrev_b32_e32 v216, 16, v210
	v_and_b32_e32 v217, 0xffff0000, v210
	v_pk_add_f32 v[216:217], v[80:81], v[216:217] neg_lo:[0,1] neg_hi:[0,1]
	v_pk_fma_f32 v[228:229], v[80:81], v[80:81], v[228:229]
	v_cvt_pk_bf16_f32 v214, v216, v217
	v_lshlrev_b32_e32 v216, 16, v211
	v_and_b32_e32 v217, 0xffff0000, v211
	v_pk_add_f32 v[216:217], v[82:83], v[216:217] neg_lo:[0,1] neg_hi:[0,1]
	v_pk_fma_f32 v[228:229], v[82:83], v[82:83], v[228:229]
	v_cvt_pk_bf16_f32 v215, v216, v217
	global_store_dwordx4 v[130:131], v[212:215], off offset:256
	v_add_f32_e32 v230, v228, v229
	v_mov_b32_e32 v219, v230
	s_nop 1
	v_permlane16_swap_b32_e32 v219, v230
	v_add_f32_e32 v230, v230, v219
	v_mov_b32_e32 v219, v230
	s_nop 1
	v_permlane32_swap_b32_e32 v219, v230
	v_add_f32_e32 v230, v230, v219
	v_add_co_u32_e32 v174, vcc, 0x1000, v172
	s_nop 1
	v_addc_co_u32_e32 v175, vcc, 0, v173, vcc
	s_and_saveexec_b64 s[24:25], s[14:15]
	global_store_dword v[174:175], v230, off
	s_mov_b64 exec, s[24:25]
	v_add_co_u32_e32 v168, vcc, 0x120000, v170
	s_nop 1
	v_addc_co_u32_e32 v169, vcc, 0, v171, vcc
	global_load_dwordx4 v[200:203], v[168:169], off
	global_load_dwordx4 v[204:207], v[168:169], off offset:16
	global_load_dwordx4 v[208:211], v[168:169], off offset:512
	global_load_dwordx4 v[212:215], v[168:169], off offset:528
	v_add_co_u32_e32 v128, vcc, 0x30000, v164
	s_nop 1
	v_addc_co_u32_e32 v129, vcc, 0, v165, vcc
	v_add_co_u32_e32 v130, vcc, 0x30000, v166
	s_nop 1
	v_addc_co_u32_e32 v131, vcc, 0, v167, vcc
	v_permlane16_swap_b32_e32 v76, v72
	v_permlane16_swap_b32_e32 v77, v73
	v_permlane16_swap_b32_e32 v78, v74
	v_permlane16_swap_b32_e32 v79, v75
	s_waitcnt vmcnt(21)
	v_pk_add_f32 v[76:77], v[132:133], v[76:77]
	v_pk_add_f32 v[78:79], v[134:135], v[78:79]
	s_waitcnt vmcnt(20)
	v_pk_add_f32 v[72:73], v[136:137], v[72:73]
	v_pk_add_f32 v[74:75], v[138:139], v[74:75]
	v_cvt_pk_bf16_f32 v132, v76, v77
	v_cvt_pk_bf16_f32 v133, v78, v79
	v_cvt_pk_bf16_f32 v134, v72, v73
	v_cvt_pk_bf16_f32 v135, v74, v75
	global_store_dwordx4 v[128:129], v[132:135], off
	v_lshlrev_b32_e32 v216, 16, v132
	v_and_b32_e32 v217, 0xffff0000, v132
	v_pk_add_f32 v[216:217], v[76:77], v[216:217] neg_lo:[0,1] neg_hi:[0,1]
	v_pk_mul_f32 v[228:229], v[76:77], v[76:77]
	v_cvt_pk_bf16_f32 v136, v216, v217
	v_lshlrev_b32_e32 v216, 16, v133
	v_and_b32_e32 v217, 0xffff0000, v133
	v_pk_add_f32 v[216:217], v[78:79], v[216:217] neg_lo:[0,1] neg_hi:[0,1]
	v_pk_fma_f32 v[228:229], v[78:79], v[78:79], v[228:229]
	v_cvt_pk_bf16_f32 v137, v216, v217
	v_lshlrev_b32_e32 v216, 16, v134
	v_and_b32_e32 v217, 0xffff0000, v134
	v_pk_add_f32 v[216:217], v[72:73], v[216:217] neg_lo:[0,1] neg_hi:[0,1]
	v_pk_fma_f32 v[228:229], v[72:73], v[72:73], v[228:229]
	v_cvt_pk_bf16_f32 v138, v216, v217
	v_lshlrev_b32_e32 v216, 16, v135
	v_and_b32_e32 v217, 0xffff0000, v135
	v_pk_add_f32 v[216:217], v[74:75], v[216:217] neg_lo:[0,1] neg_hi:[0,1]
	v_pk_fma_f32 v[228:229], v[74:75], v[74:75], v[228:229]
	v_cvt_pk_bf16_f32 v139, v216, v217
	global_store_dwordx4 v[130:131], v[136:139], off
	v_permlane16_swap_b32_e32 v68, v64
	v_permlane16_swap_b32_e32 v69, v65
	v_permlane16_swap_b32_e32 v70, v66
	v_permlane16_swap_b32_e32 v71, v67
	s_waitcnt vmcnt(21)
	v_pk_add_f32 v[68:69], v[140:141], v[68:69]
	v_pk_add_f32 v[70:71], v[142:143], v[70:71]
	s_waitcnt vmcnt(20)
	v_pk_add_f32 v[64:65], v[144:145], v[64:65]
	v_pk_add_f32 v[66:67], v[146:147], v[66:67]
	v_cvt_pk_bf16_f32 v140, v68, v69
	v_cvt_pk_bf16_f32 v141, v70, v71
	v_cvt_pk_bf16_f32 v142, v64, v65
	v_cvt_pk_bf16_f32 v143, v66, v67
	global_store_dwordx4 v[128:129], v[140:143], off offset:256
	v_lshlrev_b32_e32 v216, 16, v140
	v_and_b32_e32 v217, 0xffff0000, v140
	v_pk_add_f32 v[216:217], v[68:69], v[216:217] neg_lo:[0,1] neg_hi:[0,1]
	v_pk_fma_f32 v[228:229], v[68:69], v[68:69], v[228:229]
	v_cvt_pk_bf16_f32 v144, v216, v217
	v_lshlrev_b32_e32 v216, 16, v141
	v_and_b32_e32 v217, 0xffff0000, v141
	v_pk_add_f32 v[216:217], v[70:71], v[216:217] neg_lo:[0,1] neg_hi:[0,1]
	v_pk_fma_f32 v[228:229], v[70:71], v[70:71], v[228:229]
	v_cvt_pk_bf16_f32 v145, v216, v217
	v_lshlrev_b32_e32 v216, 16, v142
	v_and_b32_e32 v217, 0xffff0000, v142
	v_pk_add_f32 v[216:217], v[64:65], v[216:217] neg_lo:[0,1] neg_hi:[0,1]
	v_pk_fma_f32 v[228:229], v[64:65], v[64:65], v[228:229]
	v_cvt_pk_bf16_f32 v146, v216, v217
	v_lshlrev_b32_e32 v216, 16, v143
	v_and_b32_e32 v217, 0xffff0000, v143
	v_pk_add_f32 v[216:217], v[66:67], v[216:217] neg_lo:[0,1] neg_hi:[0,1]
	v_pk_fma_f32 v[228:229], v[66:67], v[66:67], v[228:229]
	v_cvt_pk_bf16_f32 v147, v216, v217
	global_store_dwordx4 v[130:131], v[144:147], off offset:256
	v_add_f32_e32 v230, v228, v229
	v_mov_b32_e32 v219, v230
	s_nop 1
	v_permlane16_swap_b32_e32 v219, v230
	v_add_f32_e32 v230, v230, v219
	v_mov_b32_e32 v219, v230
	s_nop 1
	v_permlane32_swap_b32_e32 v219, v230
	v_add_f32_e32 v230, v230, v219
	v_add_co_u32_e32 v174, vcc, 0x1800, v172
	s_nop 1
	v_addc_co_u32_e32 v175, vcc, 0, v173, vcc
	s_and_saveexec_b64 s[24:25], s[14:15]
	global_store_dword v[174:175], v230, off
	s_mov_b64 exec, s[24:25]
	v_add_co_u32_e32 v168, vcc, 0x140000, v170
	s_nop 1
	v_addc_co_u32_e32 v169, vcc, 0, v171, vcc
	global_load_dwordx4 v[132:135], v[168:169], off
	global_load_dwordx4 v[136:139], v[168:169], off offset:16
	global_load_dwordx4 v[140:143], v[168:169], off offset:512
	global_load_dwordx4 v[144:147], v[168:169], off offset:528
	v_add_co_u32_e32 v128, vcc, 0x80000, v164
	s_nop 1
	v_addc_co_u32_e32 v129, vcc, 0, v165, vcc
	v_add_co_u32_e32 v130, vcc, 0x80000, v166
	s_nop 1
	v_addc_co_u32_e32 v131, vcc, 0, v167, vcc
	v_permlane16_swap_b32_e32 v60, v56
	v_permlane16_swap_b32_e32 v61, v57
	v_permlane16_swap_b32_e32 v62, v58
	v_permlane16_swap_b32_e32 v63, v59
	s_waitcnt vmcnt(21)
	v_pk_add_f32 v[60:61], v[148:149], v[60:61]
	v_pk_add_f32 v[62:63], v[150:151], v[62:63]
	s_waitcnt vmcnt(20)
	v_pk_add_f32 v[56:57], v[152:153], v[56:57]
	v_pk_add_f32 v[58:59], v[154:155], v[58:59]
	v_cvt_pk_bf16_f32 v148, v60, v61
	v_cvt_pk_bf16_f32 v149, v62, v63
	v_cvt_pk_bf16_f32 v150, v56, v57
	v_cvt_pk_bf16_f32 v151, v58, v59
	global_store_dwordx4 v[128:129], v[148:151], off
	v_lshlrev_b32_e32 v216, 16, v148
	v_and_b32_e32 v217, 0xffff0000, v148
	v_pk_add_f32 v[216:217], v[60:61], v[216:217] neg_lo:[0,1] neg_hi:[0,1]
	v_pk_mul_f32 v[228:229], v[60:61], v[60:61]
	v_cvt_pk_bf16_f32 v152, v216, v217
	v_lshlrev_b32_e32 v216, 16, v149
	v_and_b32_e32 v217, 0xffff0000, v149
	v_pk_add_f32 v[216:217], v[62:63], v[216:217] neg_lo:[0,1] neg_hi:[0,1]
	v_pk_fma_f32 v[228:229], v[62:63], v[62:63], v[228:229]
	v_cvt_pk_bf16_f32 v153, v216, v217
	v_lshlrev_b32_e32 v216, 16, v150
	v_and_b32_e32 v217, 0xffff0000, v150
	v_pk_add_f32 v[216:217], v[56:57], v[216:217] neg_lo:[0,1] neg_hi:[0,1]
	v_pk_fma_f32 v[228:229], v[56:57], v[56:57], v[228:229]
	v_cvt_pk_bf16_f32 v154, v216, v217
	v_lshlrev_b32_e32 v216, 16, v151
	v_and_b32_e32 v217, 0xffff0000, v151
	v_pk_add_f32 v[216:217], v[58:59], v[216:217] neg_lo:[0,1] neg_hi:[0,1]
	v_pk_fma_f32 v[228:229], v[58:59], v[58:59], v[228:229]
	v_cvt_pk_bf16_f32 v155, v216, v217
	global_store_dwordx4 v[130:131], v[152:155], off
	v_permlane16_swap_b32_e32 v52, v48
	v_permlane16_swap_b32_e32 v53, v49
	v_permlane16_swap_b32_e32 v54, v50
	v_permlane16_swap_b32_e32 v55, v51
	s_waitcnt vmcnt(21)
	v_pk_add_f32 v[52:53], v[156:157], v[52:53]
	v_pk_add_f32 v[54:55], v[158:159], v[54:55]
	s_waitcnt vmcnt(20)
	v_pk_add_f32 v[48:49], v[160:161], v[48:49]
	v_pk_add_f32 v[50:51], v[162:163], v[50:51]
	v_cvt_pk_bf16_f32 v156, v52, v53
	v_cvt_pk_bf16_f32 v157, v54, v55
	v_cvt_pk_bf16_f32 v158, v48, v49
	v_cvt_pk_bf16_f32 v159, v50, v51
	global_store_dwordx4 v[128:129], v[156:159], off offset:256
	v_lshlrev_b32_e32 v216, 16, v156
	v_and_b32_e32 v217, 0xffff0000, v156
	v_pk_add_f32 v[216:217], v[52:53], v[216:217] neg_lo:[0,1] neg_hi:[0,1]
	v_pk_fma_f32 v[228:229], v[52:53], v[52:53], v[228:229]
	v_cvt_pk_bf16_f32 v160, v216, v217
	v_lshlrev_b32_e32 v216, 16, v157
	v_and_b32_e32 v217, 0xffff0000, v157
	v_pk_add_f32 v[216:217], v[54:55], v[216:217] neg_lo:[0,1] neg_hi:[0,1]
	v_pk_fma_f32 v[228:229], v[54:55], v[54:55], v[228:229]
	v_cvt_pk_bf16_f32 v161, v216, v217
	v_lshlrev_b32_e32 v216, 16, v158
	v_and_b32_e32 v217, 0xffff0000, v158
	v_pk_add_f32 v[216:217], v[48:49], v[216:217] neg_lo:[0,1] neg_hi:[0,1]
	v_pk_fma_f32 v[228:229], v[48:49], v[48:49], v[228:229]
	v_cvt_pk_bf16_f32 v162, v216, v217
	v_lshlrev_b32_e32 v216, 16, v159
	v_and_b32_e32 v217, 0xffff0000, v159
	v_pk_add_f32 v[216:217], v[50:51], v[216:217] neg_lo:[0,1] neg_hi:[0,1]
	v_pk_fma_f32 v[228:229], v[50:51], v[50:51], v[228:229]
	v_cvt_pk_bf16_f32 v163, v216, v217
	global_store_dwordx4 v[130:131], v[160:163], off offset:256
	v_add_f32_e32 v230, v228, v229
	v_mov_b32_e32 v219, v230
	s_nop 1
	v_permlane16_swap_b32_e32 v219, v230
	v_add_f32_e32 v230, v230, v219
	v_mov_b32_e32 v219, v230
	s_nop 1
	v_permlane32_swap_b32_e32 v219, v230
	v_add_f32_e32 v230, v230, v219
	v_add_co_u32_e32 v174, vcc, 0x4000, v172
	s_nop 1
	v_addc_co_u32_e32 v175, vcc, 0, v173, vcc
	s_and_saveexec_b64 s[24:25], s[14:15]
	global_store_dword v[174:175], v230, off
	s_mov_b64 exec, s[24:25]
	v_add_co_u32_e32 v168, vcc, 0x160000, v170
	s_nop 1
	v_addc_co_u32_e32 v169, vcc, 0, v171, vcc
	global_load_dwordx4 v[148:151], v[168:169], off
	global_load_dwordx4 v[152:155], v[168:169], off offset:16
	global_load_dwordx4 v[156:159], v[168:169], off offset:512
	global_load_dwordx4 v[160:163], v[168:169], off offset:528
	v_add_co_u32_e32 v128, vcc, 0x90000, v164
	s_nop 1
	v_addc_co_u32_e32 v129, vcc, 0, v165, vcc
	v_add_co_u32_e32 v130, vcc, 0x90000, v166
	s_nop 1
	v_addc_co_u32_e32 v131, vcc, 0, v167, vcc
	v_permlane16_swap_b32_e32 v44, v40
	v_permlane16_swap_b32_e32 v45, v41
	v_permlane16_swap_b32_e32 v46, v42
	v_permlane16_swap_b32_e32 v47, v43
	s_waitcnt vmcnt(21)
	v_pk_add_f32 v[44:45], v[200:201], v[44:45]
	v_pk_add_f32 v[46:47], v[202:203], v[46:47]
	s_waitcnt vmcnt(20)
	v_pk_add_f32 v[40:41], v[204:205], v[40:41]
	v_pk_add_f32 v[42:43], v[206:207], v[42:43]
	v_cvt_pk_bf16_f32 v200, v44, v45
	v_cvt_pk_bf16_f32 v201, v46, v47
	v_cvt_pk_bf16_f32 v202, v40, v41
	v_cvt_pk_bf16_f32 v203, v42, v43
	global_store_dwordx4 v[128:129], v[200:203], off
	v_lshlrev_b32_e32 v216, 16, v200
	v_and_b32_e32 v217, 0xffff0000, v200
	v_pk_add_f32 v[216:217], v[44:45], v[216:217] neg_lo:[0,1] neg_hi:[0,1]
	v_pk_mul_f32 v[228:229], v[44:45], v[44:45]
	v_cvt_pk_bf16_f32 v204, v216, v217
	v_lshlrev_b32_e32 v216, 16, v201
	v_and_b32_e32 v217, 0xffff0000, v201
	v_pk_add_f32 v[216:217], v[46:47], v[216:217] neg_lo:[0,1] neg_hi:[0,1]
	v_pk_fma_f32 v[228:229], v[46:47], v[46:47], v[228:229]
	v_cvt_pk_bf16_f32 v205, v216, v217
	v_lshlrev_b32_e32 v216, 16, v202
	v_and_b32_e32 v217, 0xffff0000, v202
	v_pk_add_f32 v[216:217], v[40:41], v[216:217] neg_lo:[0,1] neg_hi:[0,1]
	v_pk_fma_f32 v[228:229], v[40:41], v[40:41], v[228:229]
	v_cvt_pk_bf16_f32 v206, v216, v217
	v_lshlrev_b32_e32 v216, 16, v203
	v_and_b32_e32 v217, 0xffff0000, v203
	v_pk_add_f32 v[216:217], v[42:43], v[216:217] neg_lo:[0,1] neg_hi:[0,1]
	v_pk_fma_f32 v[228:229], v[42:43], v[42:43], v[228:229]
	v_cvt_pk_bf16_f32 v207, v216, v217
	global_store_dwordx4 v[130:131], v[204:207], off
	v_permlane16_swap_b32_e32 v36, v32
	v_permlane16_swap_b32_e32 v37, v33
	v_permlane16_swap_b32_e32 v38, v34
	v_permlane16_swap_b32_e32 v39, v35
	s_waitcnt vmcnt(21)
	v_pk_add_f32 v[36:37], v[208:209], v[36:37]
	v_pk_add_f32 v[38:39], v[210:211], v[38:39]
	s_waitcnt vmcnt(20)
	v_pk_add_f32 v[32:33], v[212:213], v[32:33]
	v_pk_add_f32 v[34:35], v[214:215], v[34:35]
	v_cvt_pk_bf16_f32 v208, v36, v37
	v_cvt_pk_bf16_f32 v209, v38, v39
	v_cvt_pk_bf16_f32 v210, v32, v33
	v_cvt_pk_bf16_f32 v211, v34, v35
	global_store_dwordx4 v[128:129], v[208:211], off offset:256
	v_lshlrev_b32_e32 v216, 16, v208
	v_and_b32_e32 v217, 0xffff0000, v208
	v_pk_add_f32 v[216:217], v[36:37], v[216:217] neg_lo:[0,1] neg_hi:[0,1]
	v_pk_fma_f32 v[228:229], v[36:37], v[36:37], v[228:229]
	v_cvt_pk_bf16_f32 v212, v216, v217
	v_lshlrev_b32_e32 v216, 16, v209
	v_and_b32_e32 v217, 0xffff0000, v209
	v_pk_add_f32 v[216:217], v[38:39], v[216:217] neg_lo:[0,1] neg_hi:[0,1]
	v_pk_fma_f32 v[228:229], v[38:39], v[38:39], v[228:229]
	v_cvt_pk_bf16_f32 v213, v216, v217
	v_lshlrev_b32_e32 v216, 16, v210
	v_and_b32_e32 v217, 0xffff0000, v210
	v_pk_add_f32 v[216:217], v[32:33], v[216:217] neg_lo:[0,1] neg_hi:[0,1]
	v_pk_fma_f32 v[228:229], v[32:33], v[32:33], v[228:229]
	v_cvt_pk_bf16_f32 v214, v216, v217
	v_lshlrev_b32_e32 v216, 16, v211
	v_and_b32_e32 v217, 0xffff0000, v211
	v_pk_add_f32 v[216:217], v[34:35], v[216:217] neg_lo:[0,1] neg_hi:[0,1]
	v_pk_fma_f32 v[228:229], v[34:35], v[34:35], v[228:229]
	v_cvt_pk_bf16_f32 v215, v216, v217
	global_store_dwordx4 v[130:131], v[212:215], off offset:256
	v_add_f32_e32 v230, v228, v229
	v_mov_b32_e32 v219, v230
	s_nop 1
	v_permlane16_swap_b32_e32 v219, v230
	v_add_f32_e32 v230, v230, v219
	v_mov_b32_e32 v219, v230
	s_nop 1
	v_permlane32_swap_b32_e32 v219, v230
	v_add_f32_e32 v230, v230, v219
	v_add_co_u32_e32 v174, vcc, 0x4800, v172
	s_nop 1
	v_addc_co_u32_e32 v175, vcc, 0, v173, vcc
	s_and_saveexec_b64 s[24:25], s[14:15]
	global_store_dword v[174:175], v230, off
	s_mov_b64 exec, s[24:25]
	v_add_co_u32_e32 v128, vcc, 0xa0000, v164
	s_nop 1
	v_addc_co_u32_e32 v129, vcc, 0, v165, vcc
	v_add_co_u32_e32 v130, vcc, 0xa0000, v166
	s_nop 1
	v_addc_co_u32_e32 v131, vcc, 0, v167, vcc
	v_permlane16_swap_b32_e32 v28, v24
	v_permlane16_swap_b32_e32 v29, v25
	v_permlane16_swap_b32_e32 v30, v26
	v_permlane16_swap_b32_e32 v31, v27
	s_waitcnt vmcnt(17)
	v_pk_add_f32 v[28:29], v[132:133], v[28:29]
	v_pk_add_f32 v[30:31], v[134:135], v[30:31]
	s_waitcnt vmcnt(16)
	v_pk_add_f32 v[24:25], v[136:137], v[24:25]
	v_pk_add_f32 v[26:27], v[138:139], v[26:27]
	v_cvt_pk_bf16_f32 v132, v28, v29
	v_cvt_pk_bf16_f32 v133, v30, v31
	v_cvt_pk_bf16_f32 v134, v24, v25
	v_cvt_pk_bf16_f32 v135, v26, v27
	global_store_dwordx4 v[128:129], v[132:135], off
	v_lshlrev_b32_e32 v216, 16, v132
	v_and_b32_e32 v217, 0xffff0000, v132
	v_pk_add_f32 v[216:217], v[28:29], v[216:217] neg_lo:[0,1] neg_hi:[0,1]
	v_pk_mul_f32 v[228:229], v[28:29], v[28:29]
	v_cvt_pk_bf16_f32 v136, v216, v217
	v_lshlrev_b32_e32 v216, 16, v133
	v_and_b32_e32 v217, 0xffff0000, v133
	v_pk_add_f32 v[216:217], v[30:31], v[216:217] neg_lo:[0,1] neg_hi:[0,1]
	v_pk_fma_f32 v[228:229], v[30:31], v[30:31], v[228:229]
	v_cvt_pk_bf16_f32 v137, v216, v217
	v_lshlrev_b32_e32 v216, 16, v134
	v_and_b32_e32 v217, 0xffff0000, v134
	v_pk_add_f32 v[216:217], v[24:25], v[216:217] neg_lo:[0,1] neg_hi:[0,1]
	v_pk_fma_f32 v[228:229], v[24:25], v[24:25], v[228:229]
	v_cvt_pk_bf16_f32 v138, v216, v217
	v_lshlrev_b32_e32 v216, 16, v135
	v_and_b32_e32 v217, 0xffff0000, v135
	v_pk_add_f32 v[216:217], v[26:27], v[216:217] neg_lo:[0,1] neg_hi:[0,1]
	v_pk_fma_f32 v[228:229], v[26:27], v[26:27], v[228:229]
	v_cvt_pk_bf16_f32 v139, v216, v217
	global_store_dwordx4 v[130:131], v[136:139], off
	v_permlane16_swap_b32_e32 v20, v16
	v_permlane16_swap_b32_e32 v21, v17
	v_permlane16_swap_b32_e32 v22, v18
	v_permlane16_swap_b32_e32 v23, v19
	s_waitcnt vmcnt(17)
	v_pk_add_f32 v[20:21], v[140:141], v[20:21]
	v_pk_add_f32 v[22:23], v[142:143], v[22:23]
	s_waitcnt vmcnt(16)
	v_pk_add_f32 v[16:17], v[144:145], v[16:17]
	v_pk_add_f32 v[18:19], v[146:147], v[18:19]
	v_cvt_pk_bf16_f32 v140, v20, v21
	v_cvt_pk_bf16_f32 v141, v22, v23
	v_cvt_pk_bf16_f32 v142, v16, v17
	v_cvt_pk_bf16_f32 v143, v18, v19
	global_store_dwordx4 v[128:129], v[140:143], off offset:256
	v_lshlrev_b32_e32 v216, 16, v140
	v_and_b32_e32 v217, 0xffff0000, v140
	v_pk_add_f32 v[216:217], v[20:21], v[216:217] neg_lo:[0,1] neg_hi:[0,1]
	v_pk_fma_f32 v[228:229], v[20:21], v[20:21], v[228:229]
	v_cvt_pk_bf16_f32 v144, v216, v217
	v_lshlrev_b32_e32 v216, 16, v141
	v_and_b32_e32 v217, 0xffff0000, v141
	v_pk_add_f32 v[216:217], v[22:23], v[216:217] neg_lo:[0,1] neg_hi:[0,1]
	v_pk_fma_f32 v[228:229], v[22:23], v[22:23], v[228:229]
	v_cvt_pk_bf16_f32 v145, v216, v217
	v_lshlrev_b32_e32 v216, 16, v142
	v_and_b32_e32 v217, 0xffff0000, v142
	v_pk_add_f32 v[216:217], v[16:17], v[216:217] neg_lo:[0,1] neg_hi:[0,1]
	v_pk_fma_f32 v[228:229], v[16:17], v[16:17], v[228:229]
	v_cvt_pk_bf16_f32 v146, v216, v217
	v_lshlrev_b32_e32 v216, 16, v143
	v_and_b32_e32 v217, 0xffff0000, v143
	v_pk_add_f32 v[216:217], v[18:19], v[216:217] neg_lo:[0,1] neg_hi:[0,1]
	v_pk_fma_f32 v[228:229], v[18:19], v[18:19], v[228:229]
	v_cvt_pk_bf16_f32 v147, v216, v217
	global_store_dwordx4 v[130:131], v[144:147], off offset:256
	v_add_f32_e32 v230, v228, v229
	v_mov_b32_e32 v219, v230
	s_nop 1
	v_permlane16_swap_b32_e32 v219, v230
	v_add_f32_e32 v230, v230, v219
	v_mov_b32_e32 v219, v230
	s_nop 1
	v_permlane32_swap_b32_e32 v219, v230
	v_add_f32_e32 v230, v230, v219
	v_add_co_u32_e32 v174, vcc, 0x5000, v172
	s_nop 1
	v_addc_co_u32_e32 v175, vcc, 0, v173, vcc
	s_and_saveexec_b64 s[24:25], s[14:15]
	global_store_dword v[174:175], v230, off
	s_mov_b64 exec, s[24:25]
	v_add_co_u32_e32 v128, vcc, 0xb0000, v164
	s_nop 1
	v_addc_co_u32_e32 v129, vcc, 0, v165, vcc
	v_add_co_u32_e32 v130, vcc, 0xb0000, v166
	s_nop 1
	v_addc_co_u32_e32 v131, vcc, 0, v167, vcc
	v_permlane16_swap_b32_e32 v12, v8
	v_permlane16_swap_b32_e32 v13, v9
	v_permlane16_swap_b32_e32 v14, v10
	v_permlane16_swap_b32_e32 v15, v11
	s_waitcnt vmcnt(13)
	v_pk_add_f32 v[12:13], v[148:149], v[12:13]
	v_pk_add_f32 v[14:15], v[150:151], v[14:15]
	s_waitcnt vmcnt(12)
	v_pk_add_f32 v[8:9], v[152:153], v[8:9]
	v_pk_add_f32 v[10:11], v[154:155], v[10:11]
	v_cvt_pk_bf16_f32 v148, v12, v13
	v_cvt_pk_bf16_f32 v149, v14, v15
	v_cvt_pk_bf16_f32 v150, v8, v9
	v_cvt_pk_bf16_f32 v151, v10, v11
	global_store_dwordx4 v[128:129], v[148:151], off
	v_lshlrev_b32_e32 v216, 16, v148
	v_and_b32_e32 v217, 0xffff0000, v148
	v_pk_add_f32 v[216:217], v[12:13], v[216:217] neg_lo:[0,1] neg_hi:[0,1]
	v_pk_mul_f32 v[228:229], v[12:13], v[12:13]
	v_cvt_pk_bf16_f32 v152, v216, v217
	v_lshlrev_b32_e32 v216, 16, v149
	v_and_b32_e32 v217, 0xffff0000, v149
	v_pk_add_f32 v[216:217], v[14:15], v[216:217] neg_lo:[0,1] neg_hi:[0,1]
	v_pk_fma_f32 v[228:229], v[14:15], v[14:15], v[228:229]
	v_cvt_pk_bf16_f32 v153, v216, v217
	v_lshlrev_b32_e32 v216, 16, v150
	v_and_b32_e32 v217, 0xffff0000, v150
	v_pk_add_f32 v[216:217], v[8:9], v[216:217] neg_lo:[0,1] neg_hi:[0,1]
	v_pk_fma_f32 v[228:229], v[8:9], v[8:9], v[228:229]
	v_cvt_pk_bf16_f32 v154, v216, v217
	v_lshlrev_b32_e32 v216, 16, v151
	v_and_b32_e32 v217, 0xffff0000, v151
	v_pk_add_f32 v[216:217], v[10:11], v[216:217] neg_lo:[0,1] neg_hi:[0,1]
	v_pk_fma_f32 v[228:229], v[10:11], v[10:11], v[228:229]
	v_cvt_pk_bf16_f32 v155, v216, v217
	global_store_dwordx4 v[130:131], v[152:155], off
	v_permlane16_swap_b32_e32 v4, v0
	v_permlane16_swap_b32_e32 v5, v1
	v_permlane16_swap_b32_e32 v6, v2
	v_permlane16_swap_b32_e32 v7, v3
	s_waitcnt vmcnt(13)
	v_pk_add_f32 v[4:5], v[156:157], v[4:5]
	v_pk_add_f32 v[6:7], v[158:159], v[6:7]
	s_waitcnt vmcnt(12)
	v_pk_add_f32 v[0:1], v[160:161], v[0:1]
	v_pk_add_f32 v[2:3], v[162:163], v[2:3]
	v_cvt_pk_bf16_f32 v156, v4, v5
	v_cvt_pk_bf16_f32 v157, v6, v7
	v_cvt_pk_bf16_f32 v158, v0, v1
	v_cvt_pk_bf16_f32 v159, v2, v3
	global_store_dwordx4 v[128:129], v[156:159], off offset:256
	v_lshlrev_b32_e32 v216, 16, v156
	v_and_b32_e32 v217, 0xffff0000, v156
	v_pk_add_f32 v[216:217], v[4:5], v[216:217] neg_lo:[0,1] neg_hi:[0,1]
	v_pk_fma_f32 v[228:229], v[4:5], v[4:5], v[228:229]
	v_cvt_pk_bf16_f32 v160, v216, v217
	v_lshlrev_b32_e32 v216, 16, v157
	v_and_b32_e32 v217, 0xffff0000, v157
	v_pk_add_f32 v[216:217], v[6:7], v[216:217] neg_lo:[0,1] neg_hi:[0,1]
	v_pk_fma_f32 v[228:229], v[6:7], v[6:7], v[228:229]
	v_cvt_pk_bf16_f32 v161, v216, v217
	v_lshlrev_b32_e32 v216, 16, v158
	v_and_b32_e32 v217, 0xffff0000, v158
	v_pk_add_f32 v[216:217], v[0:1], v[216:217] neg_lo:[0,1] neg_hi:[0,1]
	v_pk_fma_f32 v[228:229], v[0:1], v[0:1], v[228:229]
	v_cvt_pk_bf16_f32 v162, v216, v217
	v_lshlrev_b32_e32 v216, 16, v159
	v_and_b32_e32 v217, 0xffff0000, v159
	v_pk_add_f32 v[216:217], v[2:3], v[216:217] neg_lo:[0,1] neg_hi:[0,1]
	v_pk_fma_f32 v[228:229], v[2:3], v[2:3], v[228:229]
	v_cvt_pk_bf16_f32 v163, v216, v217
	global_store_dwordx4 v[130:131], v[160:163], off offset:256
	v_add_f32_e32 v230, v228, v229
	v_mov_b32_e32 v219, v230
	s_nop 1
	v_permlane16_swap_b32_e32 v219, v230
	v_add_f32_e32 v230, v230, v219
	v_mov_b32_e32 v219, v230
	s_nop 1
	v_permlane32_swap_b32_e32 v219, v230
	v_add_f32_e32 v230, v230, v219
	v_add_co_u32_e32 v174, vcc, 0x5800, v172
	s_nop 1
	v_addc_co_u32_e32 v175, vcc, 0, v173, vcc
	s_and_saveexec_b64 s[24:25], s[14:15]
	global_store_dword v[174:175], v230, off
	s_mov_b64 exec, s[24:25]
	s_andn2_b64 vcc, exec, s[4:5]
	s_mov_b64 s[2:3], -1
	s_cbranch_vccnz .LBB0_42
	s_branch .LBB0_88

.LBB0_294:
	v_lshl_add_u32 v136, s42, 8, v214
	v_lshl_or_b32 v134, s41, 8, v216
	v_ashrrev_i32_e32 v137, 31, v136
	v_lshlrev_b64 v[138:139], 11, v[136:137]
	v_ashrrev_i32_e32 v135, 31, v134
	v_lshl_add_u64 v[212:213], v[138:139], 0, v[134:135]
	v_lshlrev_b64 v[138:139], 1, v[212:213]
	v_lshl_add_u64 v[140:141], s[94:95], 0, v[138:139]
	s_mov_b32 s8, 0x10000
	v_add_co_u32_e32 v142, vcc, s8, v140
	v_lshl_add_u64 v[138:139], s[10:11], 0, v[138:139]
	s_nop 0
	v_addc_co_u32_e32 v143, vcc, 0, v141, vcc
	s_and_b64 vcc, exec, s[12:13]
	s_cbranch_vccnz .Lnew_resB
	s_branch .Lnew_resB2
	v_add_co_u32_e32 v144, vcc, s8, v138
	s_mov_b32 s8, 0x20000
	s_nop 0
	v_addc_co_u32_e32 v145, vcc, 0, v139, vcc
	global_load_dwordx2 v[218:219], v[140:141], off
	global_load_dwordx2 v[228:229], v[138:139], off
	global_load_dwordx2 v[210:211], v[140:141], off offset:32
	global_load_dwordx2 v[208:209], v[138:139], off offset:32
	global_load_dwordx2 v[206:207], v[140:141], off offset:256
	global_load_dwordx2 v[204:205], v[138:139], off offset:256
	global_load_dwordx2 v[200:201], v[140:141], off offset:288
	global_load_dwordx2 v[202:203], v[138:139], off offset:288
	global_load_dwordx2 v[196:197], v[142:143], off
	global_load_dwordx2 v[198:199], v[144:145], off
	global_load_dwordx2 v[194:195], v[142:143], off offset:32
	global_load_dwordx2 v[192:193], v[144:145], off offset:32
	global_load_dwordx2 v[190:191], v[142:143], off offset:256
	global_load_dwordx2 v[188:189], v[144:145], off offset:256
	global_load_dwordx2 v[174:175], v[142:143], off offset:288
	global_load_dwordx2 v[186:187], v[144:145], off offset:288
	v_add_co_u32_e32 v142, vcc, s8, v140
	s_waitcnt vmcnt(0)
	v_lshlrev_b32_e32 v230, 16, v218
	v_addc_co_u32_e32 v143, vcc, 0, v141, vcc
	v_add_co_u32_e32 v144, vcc, s8, v138
	s_mov_b32 s8, 0x30000
	s_nop 0
	v_addc_co_u32_e32 v145, vcc, 0, v139, vcc
	global_load_dwordx2 v[170:171], v[142:143], off
	global_load_dwordx2 v[172:173], v[144:145], off
	global_load_dwordx2 v[168:169], v[142:143], off offset:32
	global_load_dwordx2 v[166:167], v[144:145], off offset:32
	global_load_dwordx2 v[164:165], v[142:143], off offset:256
	global_load_dwordx2 v[162:163], v[144:145], off offset:256
	global_load_dwordx2 v[158:159], v[142:143], off offset:288
	global_load_dwordx2 v[160:161], v[144:145], off offset:288
	v_add_co_u32_e32 v142, vcc, s8, v140
	v_and_b32_e32 v231, 0xffff0000, v218
	s_nop 0
	v_addc_co_u32_e32 v143, vcc, 0, v141, vcc
	v_add_co_u32_e32 v144, vcc, s8, v138
	global_load_dwordx2 v[154:155], v[142:143], off
	s_nop 0
	v_addc_co_u32_e32 v145, vcc, 0, v139, vcc
	global_load_dwordx2 v[156:157], v[144:145], off
	global_load_dwordx2 v[152:153], v[142:143], off offset:32
	global_load_dwordx2 v[150:151], v[144:145], off offset:32
	global_load_dwordx2 v[148:149], v[142:143], off offset:256
	global_load_dwordx2 v[146:147], v[144:145], off offset:256
	s_nop 0
	global_load_dwordx2 v[142:143], v[142:143], off offset:288
	s_nop 0
	global_load_dwordx2 v[144:145], v[144:145], off offset:288
	v_lshlrev_b32_e32 v236, 16, v228
	v_and_b32_e32 v237, 0xffff0000, v228
	v_lshlrev_b32_e32 v218, 16, v219
	v_and_b32_e32 v219, 0xffff0000, v219
	v_lshlrev_b32_e32 v228, 16, v229
	v_and_b32_e32 v229, 0xffff0000, v229
	v_pk_add_f32 v[230:231], v[230:231], v[236:237]
	v_pk_add_f32 v[218:219], v[218:219], v[228:229]
	v_pk_add_f32 v[124:125], v[124:125], v[230:231]
	v_pk_add_f32 v[126:127], v[126:127], v[218:219]
	s_mov_b64 s[8:9], -1
	s_and_b64 vcc, exec, s[12:13]
	s_cbranch_vccz .LBB0_296
	v_cvt_pk_bf16_f32 v218, v124, v125
	v_cvt_pk_bf16_f32 v219, v126, v127
	v_lshlrev_b32_e32 v228, 16, v218
	v_and_b32_e32 v229, 0xffff0000, v218
	v_lshlrev_b32_e32 v230, 16, v219
	v_and_b32_e32 v231, 0xffff0000, v219
	global_store_dwordx2 v[140:141], v[218:219], off
	v_sub_f32_e32 v219, v127, v231
	v_sub_f32_e32 v230, v126, v230
	v_sub_f32_e32 v218, v125, v229
	v_sub_f32_e32 v228, v124, v228
	v_cvt_pk_bf16_f32 v218, v228, v218
	v_cvt_pk_bf16_f32 v219, v230, v219
	global_store_dwordx2 v[138:139], v[218:219], off
	v_pk_mul_f32 v[218:219], v[126:127], v[126:127]
	v_pk_mul_f32 v[228:229], v[124:125], v[124:125]
	s_mov_b64 s[8:9], 0
	v_pk_mov_b32 v[230:231], v[228:229], v[218:219] op_sel:[1,0]
	v_mov_b32_e32 v229, v219
	v_pk_add_f32 v[218:219], v[230:231], v[228:229]
	s_nop 0
	v_add_f32_e32 v218, v218, v219

.Lnew_resB2:
	v_and_b32_e32 v236, 16, v225
	v_readlane_b32 s24, v255, 35
	v_readlane_b32 s25, v255, 36
	v_lshrrev_b32_e32 v237, 1, v236
	v_add_u32_e32 v236, v236, v237
	v_add_co_u32_e32 v204, vcc, v140, v236
	s_lshl_b32 s20, s41, 4
	s_nop 0
	v_addc_co_u32_e32 v205, vcc, 0, v141, vcc
	v_add_co_u32_e32 v206, vcc, v138, v236
	s_lshl_b32 s21, s35, 2
	s_nop 0
	v_addc_co_u32_e32 v207, vcc, 0, v139, vcc
	s_add_i32 s20, s20, s21
	v_lshlrev_b32_e32 v237, 1, v236
	v_lshl_add_u64 v[134:135], v[212:213], 2, s[84:85]
	s_nop 0
	v_add_co_u32_e32 v134, vcc, v134, v237
	s_nop 1
	v_addc_co_u32_e32 v135, vcc, 0, v135, vcc
	v_mov_b32_e32 v208, v204
	v_mov_b32_e32 v209, v205
	v_mov_b32_e32 v210, v206
	v_mov_b32_e32 v211, v207
	global_load_dwordx4 v[144:147], v[208:209], off
	global_load_dwordx4 v[148:151], v[210:211], off
	global_load_dwordx4 v[152:155], v[208:209], off offset:256
	global_load_dwordx4 v[156:159], v[210:211], off offset:256
	v_add_co_u32_e32 v208, vcc, 0x10000, v204
	s_nop 1
	v_addc_co_u32_e32 v209, vcc, 0, v205, vcc
	v_add_co_u32_e32 v210, vcc, 0x10000, v206
	s_nop 1
	v_addc_co_u32_e32 v211, vcc, 0, v207, vcc
	global_load_dwordx4 v[160:163], v[208:209], off
	global_load_dwordx4 v[164:167], v[210:211], off
	global_load_dwordx4 v[168:171], v[208:209], off offset:256
	global_load_dwordx4 v[172:175], v[210:211], off offset:256
	v_add_co_u32_e32 v208, vcc, 0x20000, v204
	s_nop 1
	v_addc_co_u32_e32 v209, vcc, 0, v205, vcc
	v_add_co_u32_e32 v210, vcc, 0x20000, v206
	s_nop 1
	v_addc_co_u32_e32 v211, vcc, 0, v207, vcc
	global_load_dwordx4 v[188:191], v[208:209], off
	global_load_dwordx4 v[192:195], v[210:211], off
	global_load_dwordx4 v[196:199], v[208:209], off offset:256
	global_load_dwordx4 v[200:203], v[210:211], off offset:256
	v_mov_b32_e32 v142, v134
	v_mov_b32_e32 v143, v135
	v_permlane16_swap_b32_e32 v124, v120
	v_permlane16_swap_b32_e32 v125, v121
	v_permlane16_swap_b32_e32 v126, v122
	v_permlane16_swap_b32_e32 v127, v123
	s_waitcnt vmcnt(11)
	v_lshlrev_b32_e32 v218, 16, v144
	v_and_b32_e32 v219, 0xffff0000, v144
	s_waitcnt vmcnt(10)
	v_lshlrev_b32_e32 v228, 16, v148
	v_and_b32_e32 v229, 0xffff0000, v148
	v_lshlrev_b32_e32 v208, 16, v145
	v_and_b32_e32 v209, 0xffff0000, v145
	v_lshlrev_b32_e32 v210, 16, v149
	v_and_b32_e32 v211, 0xffff0000, v149
	v_pk_add_f32 v[218:219], v[218:219], v[228:229]
	v_pk_add_f32 v[208:209], v[208:209], v[210:211]
	v_pk_add_f32 v[124:125], v[218:219], v[124:125]
	v_pk_add_f32 v[126:127], v[208:209], v[126:127]
	v_lshlrev_b32_e32 v218, 16, v146
	v_and_b32_e32 v219, 0xffff0000, v146
	v_lshlrev_b32_e32 v228, 16, v150
	v_and_b32_e32 v229, 0xffff0000, v150
	v_lshlrev_b32_e32 v208, 16, v147
	v_and_b32_e32 v209, 0xffff0000, v147
	v_lshlrev_b32_e32 v210, 16, v151
	v_and_b32_e32 v211, 0xffff0000, v151
	v_pk_add_f32 v[218:219], v[218:219], v[228:229]
	v_pk_add_f32 v[208:209], v[208:209], v[210:211]
	v_pk_add_f32 v[120:121], v[218:219], v[120:121]
	v_pk_add_f32 v[122:123], v[208:209], v[122:123]
	global_store_dwordx4 v[142:143], v[124:127], off
	global_store_dwordx4 v[142:143], v[120:123], off offset:16
	v_permlane16_swap_b32_e32 v116, v112
	v_permlane16_swap_b32_e32 v117, v113
	v_permlane16_swap_b32_e32 v118, v114
	v_permlane16_swap_b32_e32 v119, v115
	s_waitcnt vmcnt(11)
	v_lshlrev_b32_e32 v218, 16, v152
	v_and_b32_e32 v219, 0xffff0000, v152
	s_waitcnt vmcnt(10)
	v_lshlrev_b32_e32 v228, 16, v156
	v_and_b32_e32 v229, 0xffff0000, v156
	v_lshlrev_b32_e32 v208, 16, v153
	v_and_b32_e32 v209, 0xffff0000, v153
	v_lshlrev_b32_e32 v210, 16, v157
	v_and_b32_e32 v211, 0xffff0000, v157
	v_pk_add_f32 v[218:219], v[218:219], v[228:229]
	v_pk_add_f32 v[208:209], v[208:209], v[210:211]
	v_pk_add_f32 v[116:117], v[218:219], v[116:117]
	v_pk_add_f32 v[118:119], v[208:209], v[118:119]
	v_lshlrev_b32_e32 v218, 16, v154
	v_and_b32_e32 v219, 0xffff0000, v154
	v_lshlrev_b32_e32 v228, 16, v158
	v_and_b32_e32 v229, 0xffff0000, v158
	v_lshlrev_b32_e32 v208, 16, v155
	v_and_b32_e32 v209, 0xffff0000, v155
	v_lshlrev_b32_e32 v210, 16, v159
	v_and_b32_e32 v211, 0xffff0000, v159
	v_pk_add_f32 v[218:219], v[218:219], v[228:229]
	v_pk_add_f32 v[208:209], v[208:209], v[210:211]
	v_pk_add_f32 v[112:113], v[218:219], v[112:113]
	v_pk_add_f32 v[114:115], v[208:209], v[114:115]
	global_store_dwordx4 v[142:143], v[116:119], off offset:512
	global_store_dwordx4 v[142:143], v[112:115], off offset:528
	v_add_co_u32_e32 v208, vcc, 0x30000, v204
	s_nop 1
	v_addc_co_u32_e32 v209, vcc, 0, v205, vcc
	v_add_co_u32_e32 v210, vcc, 0x30000, v206
	s_nop 1
	v_addc_co_u32_e32 v211, vcc, 0, v207, vcc
	global_load_dwordx4 v[144:147], v[208:209], off
	global_load_dwordx4 v[148:151], v[210:211], off
	global_load_dwordx4 v[152:155], v[208:209], off offset:256
	global_load_dwordx4 v[156:159], v[210:211], off offset:256
	v_add_co_u32_e32 v142, vcc, 0x20000, v134
	s_nop 1
	v_addc_co_u32_e32 v143, vcc, 0, v135, vcc
	v_permlane16_swap_b32_e32 v108, v104
	v_permlane16_swap_b32_e32 v109, v105
	v_permlane16_swap_b32_e32 v110, v106
	v_permlane16_swap_b32_e32 v111, v107
	s_waitcnt vmcnt(15)
	v_lshlrev_b32_e32 v218, 16, v160
	v_and_b32_e32 v219, 0xffff0000, v160
	s_waitcnt vmcnt(14)
	v_lshlrev_b32_e32 v228, 16, v164
	v_and_b32_e32 v229, 0xffff0000, v164
	v_lshlrev_b32_e32 v208, 16, v161
	v_and_b32_e32 v209, 0xffff0000, v161
	v_lshlrev_b32_e32 v210, 16, v165
	v_and_b32_e32 v211, 0xffff0000, v165
	v_pk_add_f32 v[218:219], v[218:219], v[228:229]
	v_pk_add_f32 v[208:209], v[208:209], v[210:211]
	v_pk_add_f32 v[108:109], v[218:219], v[108:109]
	v_pk_add_f32 v[110:111], v[208:209], v[110:111]
	v_lshlrev_b32_e32 v218, 16, v162
	v_and_b32_e32 v219, 0xffff0000, v162
	v_lshlrev_b32_e32 v228, 16, v166
	v_and_b32_e32 v229, 0xffff0000, v166
	v_lshlrev_b32_e32 v208, 16, v163
	v_and_b32_e32 v209, 0xffff0000, v163
	v_lshlrev_b32_e32 v210, 16, v167
	v_and_b32_e32 v211, 0xffff0000, v167
	v_pk_add_f32 v[218:219], v[218:219], v[228:229]
	v_pk_add_f32 v[208:209], v[208:209], v[210:211]
	v_pk_add_f32 v[104:105], v[218:219], v[104:105]
	v_pk_add_f32 v[106:107], v[208:209], v[106:107]
	global_store_dwordx4 v[142:143], v[108:111], off
	global_store_dwordx4 v[142:143], v[104:107], off offset:16
	v_permlane16_swap_b32_e32 v100, v96
	v_permlane16_swap_b32_e32 v101, v97
	v_permlane16_swap_b32_e32 v102, v98
	v_permlane16_swap_b32_e32 v103, v99
	s_waitcnt vmcnt(15)
	v_lshlrev_b32_e32 v218, 16, v168
	v_and_b32_e32 v219, 0xffff0000, v168
	s_waitcnt vmcnt(14)
	v_lshlrev_b32_e32 v228, 16, v172
	v_and_b32_e32 v229, 0xffff0000, v172
	v_lshlrev_b32_e32 v208, 16, v169
	v_and_b32_e32 v209, 0xffff0000, v169
	v_lshlrev_b32_e32 v210, 16, v173
	v_and_b32_e32 v211, 0xffff0000, v173
	v_pk_add_f32 v[218:219], v[218:219], v[228:229]
	v_pk_add_f32 v[208:209], v[208:209], v[210:211]
	v_pk_add_f32 v[100:101], v[218:219], v[100:101]
	v_pk_add_f32 v[102:103], v[208:209], v[102:103]
	v_lshlrev_b32_e32 v218, 16, v170
	v_and_b32_e32 v219, 0xffff0000, v170
	v_lshlrev_b32_e32 v228, 16, v174
	v_and_b32_e32 v229, 0xffff0000, v174
	v_lshlrev_b32_e32 v208, 16, v171
	v_and_b32_e32 v209, 0xffff0000, v171
	v_lshlrev_b32_e32 v210, 16, v175
	v_and_b32_e32 v211, 0xffff0000, v175
	v_pk_add_f32 v[218:219], v[218:219], v[228:229]
	v_pk_add_f32 v[208:209], v[208:209], v[210:211]
	v_pk_add_f32 v[96:97], v[218:219], v[96:97]
	v_pk_add_f32 v[98:99], v[208:209], v[98:99]
	global_store_dwordx4 v[142:143], v[100:103], off offset:512
	global_store_dwordx4 v[142:143], v[96:99], off offset:528
	v_add_co_u32_e32 v208, vcc, 0x80000, v204
	s_nop 1
	v_addc_co_u32_e32 v209, vcc, 0, v205, vcc
	v_add_co_u32_e32 v210, vcc, 0x80000, v206
	s_nop 1
	v_addc_co_u32_e32 v211, vcc, 0, v207, vcc
	global_load_dwordx4 v[160:163], v[208:209], off
	global_load_dwordx4 v[164:167], v[210:211], off
	global_load_dwordx4 v[168:171], v[208:209], off offset:256
	global_load_dwordx4 v[172:175], v[210:211], off offset:256
	v_add_co_u32_e32 v142, vcc, 0x40000, v134
	s_nop 1
	v_addc_co_u32_e32 v143, vcc, 0, v135, vcc
	v_permlane16_swap_b32_e32 v92, v88
	v_permlane16_swap_b32_e32 v93, v89
	v_permlane16_swap_b32_e32 v94, v90
	v_permlane16_swap_b32_e32 v95, v91
	s_waitcnt vmcnt(19)
	v_lshlrev_b32_e32 v218, 16, v188
	v_and_b32_e32 v219, 0xffff0000, v188
	s_waitcnt vmcnt(18)
	v_lshlrev_b32_e32 v228, 16, v192
	v_and_b32_e32 v229, 0xffff0000, v192
	v_lshlrev_b32_e32 v208, 16, v189
	v_and_b32_e32 v209, 0xffff0000, v189
	v_lshlrev_b32_e32 v210, 16, v193
	v_and_b32_e32 v211, 0xffff0000, v193
	v_pk_add_f32 v[218:219], v[218:219], v[228:229]
	v_pk_add_f32 v[208:209], v[208:209], v[210:211]
	v_pk_add_f32 v[92:93], v[218:219], v[92:93]
	v_pk_add_f32 v[94:95], v[208:209], v[94:95]
	v_lshlrev_b32_e32 v218, 16, v190
	v_and_b32_e32 v219, 0xffff0000, v190
	v_lshlrev_b32_e32 v228, 16, v194
	v_and_b32_e32 v229, 0xffff0000, v194
	v_lshlrev_b32_e32 v208, 16, v191
	v_and_b32_e32 v209, 0xffff0000, v191
	v_lshlrev_b32_e32 v210, 16, v195
	v_and_b32_e32 v211, 0xffff0000, v195
	v_pk_add_f32 v[218:219], v[218:219], v[228:229]
	v_pk_add_f32 v[208:209], v[208:209], v[210:211]
	v_pk_add_f32 v[88:89], v[218:219], v[88:89]
	v_pk_add_f32 v[90:91], v[208:209], v[90:91]
	global_store_dwordx4 v[142:143], v[92:95], off
	global_store_dwordx4 v[142:143], v[88:91], off offset:16
	v_permlane16_swap_b32_e32 v84, v80
	v_permlane16_swap_b32_e32 v85, v81
	v_permlane16_swap_b32_e32 v86, v82
	v_permlane16_swap_b32_e32 v87, v83
	s_waitcnt vmcnt(19)
	v_lshlrev_b32_e32 v218, 16, v196
	v_and_b32_e32 v219, 0xffff0000, v196
	s_waitcnt vmcnt(18)
	v_lshlrev_b32_e32 v228, 16, v200
	v_and_b32_e32 v229, 0xffff0000, v200
	v_lshlrev_b32_e32 v208, 16, v197
	v_and_b32_e32 v209, 0xffff0000, v197
	v_lshlrev_b32_e32 v210, 16, v201
	v_and_b32_e32 v211, 0xffff0000, v201
	v_pk_add_f32 v[218:219], v[218:219], v[228:229]
	v_pk_add_f32 v[208:209], v[208:209], v[210:211]
	v_pk_add_f32 v[84:85], v[218:219], v[84:85]
	v_pk_add_f32 v[86:87], v[208:209], v[86:87]
	v_lshlrev_b32_e32 v218, 16, v198
	v_and_b32_e32 v219, 0xffff0000, v198
	v_lshlrev_b32_e32 v228, 16, v202
	v_and_b32_e32 v229, 0xffff0000, v202
	v_lshlrev_b32_e32 v208, 16, v199
	v_and_b32_e32 v209, 0xffff0000, v199
	v_lshlrev_b32_e32 v210, 16, v203
	v_and_b32_e32 v211, 0xffff0000, v203
	v_pk_add_f32 v[218:219], v[218:219], v[228:229]
	v_pk_add_f32 v[208:209], v[208:209], v[210:211]
	v_pk_add_f32 v[80:81], v[218:219], v[80:81]
	v_pk_add_f32 v[82:83], v[208:209], v[82:83]
	global_store_dwordx4 v[142:143], v[84:87], off offset:512
	global_store_dwordx4 v[142:143], v[80:83], off offset:528
	v_add_co_u32_e32 v208, vcc, 0x90000, v204
	s_nop 1
	v_addc_co_u32_e32 v209, vcc, 0, v205, vcc
	v_add_co_u32_e32 v210, vcc, 0x90000, v206
	s_nop 1
	v_addc_co_u32_e32 v211, vcc, 0, v207, vcc
	global_load_dwordx4 v[188:191], v[208:209], off
	global_load_dwordx4 v[192:195], v[210:211], off
	global_load_dwordx4 v[196:199], v[208:209], off offset:256
	global_load_dwordx4 v[200:203], v[210:211], off offset:256
	v_add_co_u32_e32 v142, vcc, 0x60000, v134
	s_nop 1
	v_addc_co_u32_e32 v143, vcc, 0, v135, vcc
	v_permlane16_swap_b32_e32 v76, v72
	v_permlane16_swap_b32_e32 v77, v73
	v_permlane16_swap_b32_e32 v78, v74
	v_permlane16_swap_b32_e32 v79, v75
	s_waitcnt vmcnt(19)
	v_lshlrev_b32_e32 v218, 16, v144
	v_and_b32_e32 v219, 0xffff0000, v144
	s_waitcnt vmcnt(18)
	v_lshlrev_b32_e32 v228, 16, v148
	v_and_b32_e32 v229, 0xffff0000, v148
	v_lshlrev_b32_e32 v208, 16, v145
	v_and_b32_e32 v209, 0xffff0000, v145
	v_lshlrev_b32_e32 v210, 16, v149
	v_and_b32_e32 v211, 0xffff0000, v149
	v_pk_add_f32 v[218:219], v[218:219], v[228:229]
	v_pk_add_f32 v[208:209], v[208:209], v[210:211]
	v_pk_add_f32 v[76:77], v[218:219], v[76:77]
	v_pk_add_f32 v[78:79], v[208:209], v[78:79]
	v_lshlrev_b32_e32 v218, 16, v146
	v_and_b32_e32 v219, 0xffff0000, v146
	v_lshlrev_b32_e32 v228, 16, v150
	v_and_b32_e32 v229, 0xffff0000, v150
	v_lshlrev_b32_e32 v208, 16, v147
	v_and_b32_e32 v209, 0xffff0000, v147
	v_lshlrev_b32_e32 v210, 16, v151
	v_and_b32_e32 v211, 0xffff0000, v151
	v_pk_add_f32 v[218:219], v[218:219], v[228:229]
	v_pk_add_f32 v[208:209], v[208:209], v[210:211]
	v_pk_add_f32 v[72:73], v[218:219], v[72:73]
	v_pk_add_f32 v[74:75], v[208:209], v[74:75]
	global_store_dwordx4 v[142:143], v[76:79], off
	global_store_dwordx4 v[142:143], v[72:75], off offset:16
	v_permlane16_swap_b32_e32 v68, v64
	v_permlane16_swap_b32_e32 v69, v65
	v_permlane16_swap_b32_e32 v70, v66
	v_permlane16_swap_b32_e32 v71, v67
	s_waitcnt vmcnt(19)
	v_lshlrev_b32_e32 v218, 16, v152
	v_and_b32_e32 v219, 0xffff0000, v152
	s_waitcnt vmcnt(18)
	v_lshlrev_b32_e32 v228, 16, v156
	v_and_b32_e32 v229, 0xffff0000, v156
	v_lshlrev_b32_e32 v208, 16, v153
	v_and_b32_e32 v209, 0xffff0000, v153
	v_lshlrev_b32_e32 v210, 16, v157
	v_and_b32_e32 v211, 0xffff0000, v157
	v_pk_add_f32 v[218:219], v[218:219], v[228:229]
	v_pk_add_f32 v[208:209], v[208:209], v[210:211]
	v_pk_add_f32 v[68:69], v[218:219], v[68:69]
	v_pk_add_f32 v[70:71], v[208:209], v[70:71]
	v_lshlrev_b32_e32 v218, 16, v154
	v_and_b32_e32 v219, 0xffff0000, v154
	v_lshlrev_b32_e32 v228, 16, v158
	v_and_b32_e32 v229, 0xffff0000, v158
	v_lshlrev_b32_e32 v208, 16, v155
	v_and_b32_e32 v209, 0xffff0000, v155
	v_lshlrev_b32_e32 v210, 16, v159
	v_and_b32_e32 v211, 0xffff0000, v159
	v_pk_add_f32 v[218:219], v[218:219], v[228:229]
	v_pk_add_f32 v[208:209], v[208:209], v[210:211]
	v_pk_add_f32 v[64:65], v[218:219], v[64:65]
	v_pk_add_f32 v[66:67], v[208:209], v[66:67]
	global_store_dwordx4 v[142:143], v[68:71], off offset:512
	global_store_dwordx4 v[142:143], v[64:67], off offset:528
	v_add_co_u32_e32 v208, vcc, 0xa0000, v204
	s_nop 1
	v_addc_co_u32_e32 v209, vcc, 0, v205, vcc
	v_add_co_u32_e32 v210, vcc, 0xa0000, v206
	s_nop 1
	v_addc_co_u32_e32 v211, vcc, 0, v207, vcc
	global_load_dwordx4 v[144:147], v[208:209], off
	global_load_dwordx4 v[148:151], v[210:211], off
	global_load_dwordx4 v[152:155], v[208:209], off offset:256
	global_load_dwordx4 v[156:159], v[210:211], off offset:256
	v_add_co_u32_e32 v142, vcc, 0x100000, v134
	s_nop 1
	v_addc_co_u32_e32 v143, vcc, 0, v135, vcc
	v_permlane16_swap_b32_e32 v60, v56
	v_permlane16_swap_b32_e32 v61, v57
	v_permlane16_swap_b32_e32 v62, v58
	v_permlane16_swap_b32_e32 v63, v59
	s_waitcnt vmcnt(19)
	v_lshlrev_b32_e32 v218, 16, v160
	v_and_b32_e32 v219, 0xffff0000, v160
	s_waitcnt vmcnt(18)
	v_lshlrev_b32_e32 v228, 16, v164
	v_and_b32_e32 v229, 0xffff0000, v164
	v_lshlrev_b32_e32 v208, 16, v161
	v_and_b32_e32 v209, 0xffff0000, v161
	v_lshlrev_b32_e32 v210, 16, v165
	v_and_b32_e32 v211, 0xffff0000, v165
	v_pk_add_f32 v[218:219], v[218:219], v[228:229]
	v_pk_add_f32 v[208:209], v[208:209], v[210:211]
	v_pk_add_f32 v[60:61], v[218:219], v[60:61]
	v_pk_add_f32 v[62:63], v[208:209], v[62:63]
	v_lshlrev_b32_e32 v218, 16, v162
	v_and_b32_e32 v219, 0xffff0000, v162
	v_lshlrev_b32_e32 v228, 16, v166
	v_and_b32_e32 v229, 0xffff0000, v166
	v_lshlrev_b32_e32 v208, 16, v163
	v_and_b32_e32 v209, 0xffff0000, v163
	v_lshlrev_b32_e32 v210, 16, v167
	v_and_b32_e32 v211, 0xffff0000, v167
	v_pk_add_f32 v[218:219], v[218:219], v[228:229]
	v_pk_add_f32 v[208:209], v[208:209], v[210:211]
	v_pk_add_f32 v[56:57], v[218:219], v[56:57]
	v_pk_add_f32 v[58:59], v[208:209], v[58:59]
	global_store_dwordx4 v[142:143], v[60:63], off
	global_store_dwordx4 v[142:143], v[56:59], off offset:16
	v_permlane16_swap_b32_e32 v52, v48
	v_permlane16_swap_b32_e32 v53, v49
	v_permlane16_swap_b32_e32 v54, v50
	v_permlane16_swap_b32_e32 v55, v51
	s_waitcnt vmcnt(19)
	v_lshlrev_b32_e32 v218, 16, v168
	v_and_b32_e32 v219, 0xffff0000, v168
	s_waitcnt vmcnt(18)
	v_lshlrev_b32_e32 v228, 16, v172
	v_and_b32_e32 v229, 0xffff0000, v172
	v_lshlrev_b32_e32 v208, 16, v169
	v_and_b32_e32 v209, 0xffff0000, v169
	v_lshlrev_b32_e32 v210, 16, v173
	v_and_b32_e32 v211, 0xffff0000, v173
	v_pk_add_f32 v[218:219], v[218:219], v[228:229]
	v_pk_add_f32 v[208:209], v[208:209], v[210:211]
	v_pk_add_f32 v[52:53], v[218:219], v[52:53]
	v_pk_add_f32 v[54:55], v[208:209], v[54:55]
	v_lshlrev_b32_e32 v218, 16, v170
	v_and_b32_e32 v219, 0xffff0000, v170
	v_lshlrev_b32_e32 v228, 16, v174
	v_and_b32_e32 v229, 0xffff0000, v174
	v_lshlrev_b32_e32 v208, 16, v171
	v_and_b32_e32 v209, 0xffff0000, v171
	v_lshlrev_b32_e32 v210, 16, v175
	v_and_b32_e32 v211, 0xffff0000, v175
	v_pk_add_f32 v[218:219], v[218:219], v[228:229]
	v_pk_add_f32 v[208:209], v[208:209], v[210:211]
	v_pk_add_f32 v[48:49], v[218:219], v[48:49]
	v_pk_add_f32 v[50:51], v[208:209], v[50:51]
	global_store_dwordx4 v[142:143], v[52:55], off offset:512
	global_store_dwordx4 v[142:143], v[48:51], off offset:528
	v_add_co_u32_e32 v208, vcc, 0xb0000, v204
	s_nop 1
	v_addc_co_u32_e32 v209, vcc, 0, v205, vcc
	v_add_co_u32_e32 v210, vcc, 0xb0000, v206
	s_nop 1
	v_addc_co_u32_e32 v211, vcc, 0, v207, vcc
	global_load_dwordx4 v[160:163], v[208:209], off
	global_load_dwordx4 v[164:167], v[210:211], off
	global_load_dwordx4 v[168:171], v[208:209], off offset:256
	global_load_dwordx4 v[172:175], v[210:211], off offset:256
	v_add_co_u32_e32 v142, vcc, 0x120000, v134
	s_nop 1
	v_addc_co_u32_e32 v143, vcc, 0, v135, vcc
	v_permlane16_swap_b32_e32 v44, v40
	v_permlane16_swap_b32_e32 v45, v41
	v_permlane16_swap_b32_e32 v46, v42
	v_permlane16_swap_b32_e32 v47, v43
	s_waitcnt vmcnt(19)
	v_lshlrev_b32_e32 v218, 16, v188
	v_and_b32_e32 v219, 0xffff0000, v188
	s_waitcnt vmcnt(18)
	v_lshlrev_b32_e32 v228, 16, v192
	v_and_b32_e32 v229, 0xffff0000, v192
	v_lshlrev_b32_e32 v208, 16, v189
	v_and_b32_e32 v209, 0xffff0000, v189
	v_lshlrev_b32_e32 v210, 16, v193
	v_and_b32_e32 v211, 0xffff0000, v193
	v_pk_add_f32 v[218:219], v[218:219], v[228:229]
	v_pk_add_f32 v[208:209], v[208:209], v[210:211]
	v_pk_add_f32 v[44:45], v[218:219], v[44:45]
	v_pk_add_f32 v[46:47], v[208:209], v[46:47]
	v_lshlrev_b32_e32 v218, 16, v190
	v_and_b32_e32 v219, 0xffff0000, v190
	v_lshlrev_b32_e32 v228, 16, v194
	v_and_b32_e32 v229, 0xffff0000, v194
	v_lshlrev_b32_e32 v208, 16, v191
	v_and_b32_e32 v209, 0xffff0000, v191
	v_lshlrev_b32_e32 v210, 16, v195
	v_and_b32_e32 v211, 0xffff0000, v195
	v_pk_add_f32 v[218:219], v[218:219], v[228:229]
	v_pk_add_f32 v[208:209], v[208:209], v[210:211]
	v_pk_add_f32 v[40:41], v[218:219], v[40:41]
	v_pk_add_f32 v[42:43], v[208:209], v[42:43]
	global_store_dwordx4 v[142:143], v[44:47], off
	global_store_dwordx4 v[142:143], v[40:43], off offset:16
	v_permlane16_swap_b32_e32 v36, v32
	v_permlane16_swap_b32_e32 v37, v33
	v_permlane16_swap_b32_e32 v38, v34
	v_permlane16_swap_b32_e32 v39, v35
	s_waitcnt vmcnt(19)
	v_lshlrev_b32_e32 v218, 16, v196
	v_and_b32_e32 v219, 0xffff0000, v196
	s_waitcnt vmcnt(18)
	v_lshlrev_b32_e32 v228, 16, v200
	v_and_b32_e32 v229, 0xffff0000, v200
	v_lshlrev_b32_e32 v208, 16, v197
	v_and_b32_e32 v209, 0xffff0000, v197
	v_lshlrev_b32_e32 v210, 16, v201
	v_and_b32_e32 v211, 0xffff0000, v201
	v_pk_add_f32 v[218:219], v[218:219], v[228:229]
	v_pk_add_f32 v[208:209], v[208:209], v[210:211]
	v_pk_add_f32 v[36:37], v[218:219], v[36:37]
	v_pk_add_f32 v[38:39], v[208:209], v[38:39]
	v_lshlrev_b32_e32 v218, 16, v198
	v_and_b32_e32 v219, 0xffff0000, v198
	v_lshlrev_b32_e32 v228, 16, v202
	v_and_b32_e32 v229, 0xffff0000, v202
	v_lshlrev_b32_e32 v208, 16, v199
	v_and_b32_e32 v209, 0xffff0000, v199
	v_lshlrev_b32_e32 v210, 16, v203
	v_and_b32_e32 v211, 0xffff0000, v203
	v_pk_add_f32 v[218:219], v[218:219], v[228:229]
	v_pk_add_f32 v[208:209], v[208:209], v[210:211]
	v_pk_add_f32 v[32:33], v[218:219], v[32:33]
	v_pk_add_f32 v[34:35], v[208:209], v[34:35]
	global_store_dwordx4 v[142:143], v[36:39], off offset:512
	global_store_dwordx4 v[142:143], v[32:35], off offset:528
	v_add_co_u32_e32 v142, vcc, 0x140000, v134
	s_nop 1
	v_addc_co_u32_e32 v143, vcc, 0, v135, vcc
	v_permlane16_swap_b32_e32 v28, v24
	v_permlane16_swap_b32_e32 v29, v25
	v_permlane16_swap_b32_e32 v30, v26
	v_permlane16_swap_b32_e32 v31, v27
	s_waitcnt vmcnt(15)
	v_lshlrev_b32_e32 v218, 16, v144
	v_and_b32_e32 v219, 0xffff0000, v144
	s_waitcnt vmcnt(14)
	v_lshlrev_b32_e32 v228, 16, v148
	v_and_b32_e32 v229, 0xffff0000, v148
	v_lshlrev_b32_e32 v208, 16, v145
	v_and_b32_e32 v209, 0xffff0000, v145
	v_lshlrev_b32_e32 v210, 16, v149
	v_and_b32_e32 v211, 0xffff0000, v149
	v_pk_add_f32 v[218:219], v[218:219], v[228:229]
	v_pk_add_f32 v[208:209], v[208:209], v[210:211]
	v_pk_add_f32 v[28:29], v[218:219], v[28:29]
	v_pk_add_f32 v[30:31], v[208:209], v[30:31]
	v_lshlrev_b32_e32 v218, 16, v146
	v_and_b32_e32 v219, 0xffff0000, v146
	v_lshlrev_b32_e32 v228, 16, v150
	v_and_b32_e32 v229, 0xffff0000, v150
	v_lshlrev_b32_e32 v208, 16, v147
	v_and_b32_e32 v209, 0xffff0000, v147
	v_lshlrev_b32_e32 v210, 16, v151
	v_and_b32_e32 v211, 0xffff0000, v151
	v_pk_add_f32 v[218:219], v[218:219], v[228:229]
	v_pk_add_f32 v[208:209], v[208:209], v[210:211]
	v_pk_add_f32 v[24:25], v[218:219], v[24:25]
	v_pk_add_f32 v[26:27], v[208:209], v[26:27]
	global_store_dwordx4 v[142:143], v[28:31], off
	global_store_dwordx4 v[142:143], v[24:27], off offset:16
	v_permlane16_swap_b32_e32 v20, v16
	v_permlane16_swap_b32_e32 v21, v17
	v_permlane16_swap_b32_e32 v22, v18
	v_permlane16_swap_b32_e32 v23, v19
	s_waitcnt vmcnt(15)
	v_lshlrev_b32_e32 v218, 16, v152
	v_and_b32_e32 v219, 0xffff0000, v152
	s_waitcnt vmcnt(14)
	v_lshlrev_b32_e32 v228, 16, v156
	v_and_b32_e32 v229, 0xffff0000, v156
	v_lshlrev_b32_e32 v208, 16, v153
	v_and_b32_e32 v209, 0xffff0000, v153
	v_lshlrev_b32_e32 v210, 16, v157
	v_and_b32_e32 v211, 0xffff0000, v157
	v_pk_add_f32 v[218:219], v[218:219], v[228:229]
	v_pk_add_f32 v[208:209], v[208:209], v[210:211]
	v_pk_add_f32 v[20:21], v[218:219], v[20:21]
	v_pk_add_f32 v[22:23], v[208:209], v[22:23]
	v_lshlrev_b32_e32 v218, 16, v154
	v_and_b32_e32 v219, 0xffff0000, v154
	v_lshlrev_b32_e32 v228, 16, v158
	v_and_b32_e32 v229, 0xffff0000, v158
	v_lshlrev_b32_e32 v208, 16, v155
	v_and_b32_e32 v209, 0xffff0000, v155
	v_lshlrev_b32_e32 v210, 16, v159
	v_and_b32_e32 v211, 0xffff0000, v159
	v_pk_add_f32 v[218:219], v[218:219], v[228:229]
	v_pk_add_f32 v[208:209], v[208:209], v[210:211]
	v_pk_add_f32 v[16:17], v[218:219], v[16:17]
	v_pk_add_f32 v[18:19], v[208:209], v[18:19]
	global_store_dwordx4 v[142:143], v[20:23], off offset:512
	global_store_dwordx4 v[142:143], v[16:19], off offset:528
	v_add_co_u32_e32 v142, vcc, 0x160000, v134
	s_nop 1
	v_addc_co_u32_e32 v143, vcc, 0, v135, vcc
	v_permlane16_swap_b32_e32 v12, v8
	v_permlane16_swap_b32_e32 v13, v9
	v_permlane16_swap_b32_e32 v14, v10
	v_permlane16_swap_b32_e32 v15, v11
	s_waitcnt vmcnt(11)
	v_lshlrev_b32_e32 v218, 16, v160
	v_and_b32_e32 v219, 0xffff0000, v160
	s_waitcnt vmcnt(10)
	v_lshlrev_b32_e32 v228, 16, v164
	v_and_b32_e32 v229, 0xffff0000, v164
	v_lshlrev_b32_e32 v208, 16, v161
	v_and_b32_e32 v209, 0xffff0000, v161
	v_lshlrev_b32_e32 v210, 16, v165
	v_and_b32_e32 v211, 0xffff0000, v165
	v_pk_add_f32 v[218:219], v[218:219], v[228:229]
	v_pk_add_f32 v[208:209], v[208:209], v[210:211]
	v_pk_add_f32 v[12:13], v[218:219], v[12:13]
	v_pk_add_f32 v[14:15], v[208:209], v[14:15]
	v_lshlrev_b32_e32 v218, 16, v162
	v_and_b32_e32 v219, 0xffff0000, v162
	v_lshlrev_b32_e32 v228, 16, v166
	v_and_b32_e32 v229, 0xffff0000, v166
	v_lshlrev_b32_e32 v208, 16, v163
	v_and_b32_e32 v209, 0xffff0000, v163
	v_lshlrev_b32_e32 v210, 16, v167
	v_and_b32_e32 v211, 0xffff0000, v167
	v_pk_add_f32 v[218:219], v[218:219], v[228:229]
	v_pk_add_f32 v[208:209], v[208:209], v[210:211]
	v_pk_add_f32 v[8:9], v[218:219], v[8:9]
	v_pk_add_f32 v[10:11], v[208:209], v[10:11]
	global_store_dwordx4 v[142:143], v[12:15], off
	global_store_dwordx4 v[142:143], v[8:11], off offset:16
	v_permlane16_swap_b32_e32 v4, v0
	v_permlane16_swap_b32_e32 v5, v1
	v_permlane16_swap_b32_e32 v6, v2
	v_permlane16_swap_b32_e32 v7, v3
	s_waitcnt vmcnt(11)
	v_lshlrev_b32_e32 v218, 16, v168
	v_and_b32_e32 v219, 0xffff0000, v168
	s_waitcnt vmcnt(10)
	v_lshlrev_b32_e32 v228, 16, v172
	v_and_b32_e32 v229, 0xffff0000, v172
	v_lshlrev_b32_e32 v208, 16, v169
	v_and_b32_e32 v209, 0xffff0000, v169
	v_lshlrev_b32_e32 v210, 16, v173
	v_and_b32_e32 v211, 0xffff0000, v173
	v_pk_add_f32 v[218:219], v[218:219], v[228:229]
	v_pk_add_f32 v[208:209], v[208:209], v[210:211]
	v_pk_add_f32 v[4:5], v[218:219], v[4:5]
	v_pk_add_f32 v[6:7], v[208:209], v[6:7]
	v_lshlrev_b32_e32 v218, 16, v170
	v_and_b32_e32 v219, 0xffff0000, v170
	v_lshlrev_b32_e32 v228, 16, v174
	v_and_b32_e32 v229, 0xffff0000, v174
	v_lshlrev_b32_e32 v208, 16, v171
	v_and_b32_e32 v209, 0xffff0000, v171
	v_lshlrev_b32_e32 v210, 16, v175
	v_and_b32_e32 v211, 0xffff0000, v175
	v_pk_add_f32 v[218:219], v[218:219], v[228:229]
	v_pk_add_f32 v[208:209], v[208:209], v[210:211]
	v_pk_add_f32 v[0:1], v[218:219], v[0:1]
	v_pk_add_f32 v[2:3], v[208:209], v[2:3]
	global_store_dwordx4 v[142:143], v[4:7], off offset:512
	global_store_dwordx4 v[142:143], v[0:3], off offset:528
	s_and_b64 vcc, exec, s[6:7]
	s_mov_b64 s[6:7], -1
	s_cbranch_vccnz .LBB0_279
	s_branch .LBB0_455
